# in-proj GEMM epilogue: straight-line copy without the 16 silu blocks/branches for non-gate column tiles
# speedup vs baseline: 1.0029x; 1.0029x over previous
.Lepi_tail:
	s_andn2_b64 vcc, exec, s[0:1]
	s_mov_b64 s[0:1], -1
	s_cbranch_vccnz .LBB0_184
	s_branch .LBB0_233
.Lepi_ng:
	v_ashrrev_i32_e32 v147, 31, v146
	v_lshl_or_b32 v148, s74, 8, v155
	v_lshlrev_b64 v[150:151], 14, v[146:147]
	v_ashrrev_i32_e32 v149, 31, v148
	v_lshl_add_u64 v[150:151], s[10:11], 0, v[150:151]
	v_lshl_add_u64 v[150:151], v[148:149], 1, v[150:151]
	v_cvt_pk_bf16_f32 v124, v124, v125
	v_cvt_pk_bf16_f32 v125, v126, v127
	v_cvt_pk_bf16_f32 v126, v120, v121
	v_cvt_pk_bf16_f32 v127, v122, v123
	global_store_dwordx4 v[150:151], v[124:127], off nt
	v_cvt_pk_bf16_f32 v116, v116, v117
	v_cvt_pk_bf16_f32 v117, v118, v119
	v_cvt_pk_bf16_f32 v118, v112, v113
	v_cvt_pk_bf16_f32 v119, v114, v115
	global_store_dwordx4 v[150:151], v[116:119], off offset:256 nt
	v_or_b32_e32 v112, 16, v146
	v_ashrrev_i32_e32 v113, 31, v112
	v_lshlrev_b64 v[112:113], 14, v[112:113]
	v_lshl_add_u64 v[112:113], s[10:11], 0, v[112:113]
	v_lshl_add_u64 v[112:113], v[148:149], 1, v[112:113]
	v_cvt_pk_bf16_f32 v108, v108, v109
	v_cvt_pk_bf16_f32 v109, v110, v111
	v_cvt_pk_bf16_f32 v110, v104, v105
	v_cvt_pk_bf16_f32 v111, v106, v107
	global_store_dwordx4 v[112:113], v[108:111], off nt
	v_cvt_pk_bf16_f32 v100, v100, v101
	v_cvt_pk_bf16_f32 v101, v102, v103
	v_cvt_pk_bf16_f32 v102, v96, v97
	v_cvt_pk_bf16_f32 v103, v98, v99
	global_store_dwordx4 v[112:113], v[100:103], off offset:256 nt
	v_or_b32_e32 v96, 32, v146
	v_ashrrev_i32_e32 v97, 31, v96
	v_lshlrev_b64 v[96:97], 14, v[96:97]
	v_lshl_add_u64 v[96:97], s[10:11], 0, v[96:97]
	v_lshl_add_u64 v[96:97], v[148:149], 1, v[96:97]
	v_cvt_pk_bf16_f32 v92, v92, v93
	v_cvt_pk_bf16_f32 v93, v94, v95
	v_cvt_pk_bf16_f32 v94, v88, v89
	v_cvt_pk_bf16_f32 v95, v90, v91
	global_store_dwordx4 v[96:97], v[92:95], off nt
	v_cvt_pk_bf16_f32 v84, v84, v85
	v_cvt_pk_bf16_f32 v85, v86, v87
	v_cvt_pk_bf16_f32 v86, v80, v81
	v_cvt_pk_bf16_f32 v87, v82, v83
	global_store_dwordx4 v[96:97], v[84:87], off offset:256 nt
	v_or_b32_e32 v80, 48, v146
	v_ashrrev_i32_e32 v81, 31, v80
	v_lshlrev_b64 v[80:81], 14, v[80:81]
	v_lshl_add_u64 v[80:81], s[10:11], 0, v[80:81]
	v_lshl_add_u64 v[80:81], v[148:149], 1, v[80:81]
	v_cvt_pk_bf16_f32 v76, v76, v77
	v_cvt_pk_bf16_f32 v77, v78, v79
	v_cvt_pk_bf16_f32 v78, v72, v73
	v_cvt_pk_bf16_f32 v79, v74, v75
	global_store_dwordx4 v[80:81], v[76:79], off nt
	v_cvt_pk_bf16_f32 v68, v68, v69
	v_cvt_pk_bf16_f32 v69, v70, v71
	v_cvt_pk_bf16_f32 v70, v64, v65
	v_cvt_pk_bf16_f32 v71, v66, v67
	global_store_dwordx4 v[80:81], v[68:71], off offset:256 nt
	v_lshlrev_b64 v[64:65], 14, v[146:147]
	v_lshl_add_u64 v[64:65], s[10:11], 0, v[64:65]
	v_lshl_add_u64 v[64:65], v[148:149], 1, v[64:65]
	v_cvt_pk_bf16_f32 v60, v60, v61
	v_cvt_pk_bf16_f32 v61, v62, v63
	v_cvt_pk_bf16_f32 v62, v56, v57
	v_add_co_u32_e32 v56, vcc, 0x200000, v64
	v_cvt_pk_bf16_f32 v63, v58, v59
	s_nop 0
	v_addc_co_u32_e32 v57, vcc, 0, v65, vcc
	global_store_dwordx4 v[56:57], v[60:63], off nt
	v_lshl_add_u64 v[56:57], v[64:65], 0, s[58:59]
	v_cvt_pk_bf16_f32 v52, v52, v53
	v_cvt_pk_bf16_f32 v53, v54, v55
	v_cvt_pk_bf16_f32 v54, v48, v49
	v_cvt_pk_bf16_f32 v55, v50, v51
	global_store_dwordx4 v[56:57], v[52:55], off offset:256 nt
	v_lshlrev_b64 v[48:49], 14, v[146:147]
	v_lshl_add_u64 v[48:49], s[10:11], 0, v[48:49]
	v_lshl_add_u64 v[48:49], v[148:149], 1, v[48:49]
	v_cvt_pk_bf16_f32 v44, v44, v45
	v_cvt_pk_bf16_f32 v45, v46, v47
	v_cvt_pk_bf16_f32 v46, v40, v41
	v_add_co_u32_e32 v40, vcc, 0x240000, v48
	v_cvt_pk_bf16_f32 v47, v42, v43
	s_nop 0
	v_addc_co_u32_e32 v41, vcc, 0, v49, vcc
	global_store_dwordx4 v[40:41], v[44:47], off nt
	v_lshl_add_u64 v[40:41], v[48:49], 0, s[60:61]
	v_cvt_pk_bf16_f32 v36, v36, v37
	v_cvt_pk_bf16_f32 v37, v38, v39
	v_cvt_pk_bf16_f32 v38, v32, v33
	v_cvt_pk_bf16_f32 v39, v34, v35
	global_store_dwordx4 v[40:41], v[36:39], off offset:256 nt
	v_lshlrev_b64 v[32:33], 14, v[146:147]
	v_lshl_add_u64 v[32:33], s[10:11], 0, v[32:33]
	v_lshl_add_u64 v[32:33], v[148:149], 1, v[32:33]
	v_cvt_pk_bf16_f32 v28, v28, v29
	v_cvt_pk_bf16_f32 v29, v30, v31
	v_cvt_pk_bf16_f32 v30, v24, v25
	v_add_co_u32_e32 v24, vcc, 0x280000, v32
	v_cvt_pk_bf16_f32 v31, v26, v27
	s_nop 0
	v_addc_co_u32_e32 v25, vcc, 0, v33, vcc
	global_store_dwordx4 v[24:25], v[28:31], off nt
	v_lshl_add_u64 v[24:25], v[32:33], 0, s[62:63]
	v_cvt_pk_bf16_f32 v20, v20, v21
	v_cvt_pk_bf16_f32 v21, v22, v23
	v_cvt_pk_bf16_f32 v22, v16, v17
	v_cvt_pk_bf16_f32 v23, v18, v19
	global_store_dwordx4 v[24:25], v[20:23], off offset:256 nt
	v_lshlrev_b64 v[16:17], 14, v[146:147]
	v_lshl_add_u64 v[16:17], s[10:11], 0, v[16:17]
	v_lshl_add_u64 v[16:17], v[148:149], 1, v[16:17]
	v_cvt_pk_bf16_f32 v12, v12, v13
	v_cvt_pk_bf16_f32 v13, v14, v15
	v_cvt_pk_bf16_f32 v14, v8, v9
	v_add_co_u32_e32 v8, vcc, 0x2c0000, v16
	v_cvt_pk_bf16_f32 v15, v10, v11
	s_nop 0
	v_addc_co_u32_e32 v9, vcc, 0, v17, vcc
	global_store_dwordx4 v[8:9], v[12:15], off nt
	v_lshl_add_u64 v[8:9], v[16:17], 0, s[64:65]
	v_cvt_pk_bf16_f32 v4, v4, v5
	v_cvt_pk_bf16_f32 v5, v6, v7
	v_cvt_pk_bf16_f32 v6, v0, v1
	v_cvt_pk_bf16_f32 v7, v2, v3
	global_store_dwordx4 v[8:9], v[4:7], off offset:256 nt
	s_branch .Lepi_tail
